# UP GEMM: last K iteration issues only 6 of the 14 next-unit prefetch DMAs; 8 deferred into the epilogue after halo exports, none when no next unit
# speedup vs baseline: 1.0147x; 1.0044x over previous
.Lmy_u1_s2_last:
	s_waitcnt vmcnt(2)
	s_branch .Lmy_u1_s2_join
.Lmy_u1_s3_last:
	s_waitcnt vmcnt(6)
	s_cmp_eq_u32 s62, s98
	s_cbranch_scc0 .Lmy_u1_s3_join
	s_waitcnt vmcnt(0)
	s_branch .Lmy_u1_s3_join
.Lmy_u1_s4_last:
	s_waitcnt vmcnt(0)
	s_branch .Lmy_u1_s4_join

.LBB0_212:
	s_ashr_i32 s25, s24, 31
	s_lshl_b64 s[26:27], s[24:25], 19
	s_add_u32 s26, s45, s26
	s_addc_u32 s27, s46, s27
	s_and_b64 s[28:29], s[6:7], exec
	s_cselect_b32 s25, s27, s37
	s_cselect_b32 s31, s26, s36
	s_ashr_i32 s23, s22, 31
	s_lshl_b64 s[28:29], s[22:23], 19
	s_add_u32 s28, s47, s28
	s_addc_u32 s29, s48, s29
	s_and_b64 s[40:41], s[6:7], exec
	s_cselect_b32 s23, s29, s39
	s_cselect_b32 s35, s28, s38
	s_cselect_b32 s98, 0x7fff, 12
	s_add_u32 s60, s38, 0x100
	v_mov_b32_e32 v62, 0
	s_addc_u32 s61, s39, 0
	s_mov_b32 s62, -2
	v_mov_b32_e32 v63, v62
	v_mov_b32_e32 v64, v62
	v_mov_b32_e32 v65, v62
	v_mov_b32_e32 v30, v62
	v_mov_b32_e32 v31, v62
	v_mov_b32_e32 v32, v62
	v_mov_b32_e32 v33, v62
	v_mov_b32_e32 v50, v62
	v_mov_b32_e32 v51, v62
	v_mov_b32_e32 v52, v62
	v_mov_b32_e32 v53, v62
	v_mov_b32_e32 v26, v62
	v_mov_b32_e32 v27, v62
	v_mov_b32_e32 v28, v62
	v_mov_b32_e32 v29, v62
	v_mov_b32_e32 v118, v62
	v_mov_b32_e32 v119, v62
	v_mov_b32_e32 v120, v62
	v_mov_b32_e32 v121, v62
	v_mov_b32_e32 v10, v62
	v_mov_b32_e32 v11, v62
	v_mov_b32_e32 v12, v62
	v_mov_b32_e32 v13, v62
	v_mov_b32_e32 v126, v62
	v_mov_b32_e32 v127, v62
	v_mov_b32_e32 v128, v62
	v_mov_b32_e32 v129, v62
	v_mov_b32_e32 v102, v62
	v_mov_b32_e32 v103, v62
	v_mov_b32_e32 v104, v62
	v_mov_b32_e32 v105, v62
	v_mov_b32_e32 v42, v62
	v_mov_b32_e32 v43, v62
	v_mov_b32_e32 v44, v62
	v_mov_b32_e32 v45, v62
	v_mov_b32_e32 v46, v62
	v_mov_b32_e32 v47, v62
	v_mov_b32_e32 v48, v62
	v_mov_b32_e32 v49, v62
	v_mov_b32_e32 v14, v62
	v_mov_b32_e32 v15, v62
	v_mov_b32_e32 v16, v62
	v_mov_b32_e32 v17, v62
	v_mov_b32_e32 v122, v62
	v_mov_b32_e32 v123, v62
	v_mov_b32_e32 v124, v62
	v_mov_b32_e32 v125, v62
	v_mov_b32_e32 v6, v62
	v_mov_b32_e32 v7, v62
	v_mov_b32_e32 v8, v62
	v_mov_b32_e32 v9, v62
	v_mov_b32_e32 v130, v62
	v_mov_b32_e32 v131, v62
	v_mov_b32_e32 v132, v62
	v_mov_b32_e32 v133, v62
	v_mov_b32_e32 v106, v62
	v_mov_b32_e32 v107, v62
	v_mov_b32_e32 v108, v62
	v_mov_b32_e32 v109, v62
	v_mov_b32_e32 v110, v62
	v_mov_b32_e32 v111, v62
	v_mov_b32_e32 v112, v62
	v_mov_b32_e32 v113, v62
	v_mov_b32_e32 v38, v62
	v_mov_b32_e32 v39, v62
	v_mov_b32_e32 v40, v62
	v_mov_b32_e32 v41, v62
	v_mov_b32_e32 v114, v62
	v_mov_b32_e32 v115, v62
	v_mov_b32_e32 v116, v62
	v_mov_b32_e32 v117, v62
	v_mov_b32_e32 v158, v62
	v_mov_b32_e32 v159, v62
	v_mov_b32_e32 v160, v62
	v_mov_b32_e32 v161, v62
	v_mov_b32_e32 v18, v62
	v_mov_b32_e32 v19, v62
	v_mov_b32_e32 v20, v62
	v_mov_b32_e32 v21, v62
	v_mov_b32_e32 v146, v62
	v_mov_b32_e32 v147, v62
	v_mov_b32_e32 v148, v62
	v_mov_b32_e32 v149, v62
	v_mov_b32_e32 v134, v62
	v_mov_b32_e32 v135, v62
	v_mov_b32_e32 v136, v62
	v_mov_b32_e32 v137, v62
	v_mov_b32_e32 v54, v62
	v_mov_b32_e32 v55, v62
	v_mov_b32_e32 v56, v62
	v_mov_b32_e32 v57, v62
	v_mov_b32_e32 v66, v62
	v_mov_b32_e32 v67, v62
	v_mov_b32_e32 v68, v62
	v_mov_b32_e32 v69, v62
	v_mov_b32_e32 v34, v62
	v_mov_b32_e32 v35, v62
	v_mov_b32_e32 v36, v62
	v_mov_b32_e32 v37, v62
	v_mov_b32_e32 v162, v62
	v_mov_b32_e32 v163, v62
	v_mov_b32_e32 v164, v62
	v_mov_b32_e32 v165, v62
	v_mov_b32_e32 v22, v62
	v_mov_b32_e32 v23, v62
	v_mov_b32_e32 v24, v62
	v_mov_b32_e32 v25, v62
	v_mov_b32_e32 v150, v62
	v_mov_b32_e32 v151, v62
	v_mov_b32_e32 v152, v62
	v_mov_b32_e32 v153, v62
	v_mov_b32_e32 v138, v62
	v_mov_b32_e32 v139, v62
	v_mov_b32_e32 v140, v62
	v_mov_b32_e32 v141, v62
	v_mov_b32_e32 v142, v62
	v_mov_b32_e32 v143, v62
	v_mov_b32_e32 v144, v62
	v_mov_b32_e32 v145, v62
	v_mov_b32_e32 v58, v62
	v_mov_b32_e32 v59, v62
	v_mov_b32_e32 v60, v62
	v_mov_b32_e32 v61, v62
	v_mov_b32_e32 v154, v62
	v_mov_b32_e32 v155, v62
	v_mov_b32_e32 v156, v62
	v_mov_b32_e32 v157, v62
.LBB0_213:
	s_add_u32 s38, s36, 0x100
	s_addc_u32 s39, s37, 0
	s_add_i32 s63, 0, 0x10000
	s_cmp_eq_u32 s62, 12
	s_cselect_b32 s43, s25, s39
	s_cselect_b32 s42, s31, s38
	v_add_u32_e32 v0, s63, v232
	s_cselect_b32 s41, s23, s61
	s_cselect_b32 s40, s35, s60
	s_add_i32 s64, 0, 0x14000
	ds_read_b128 v[70:73], v0
	ds_read_b128 v[74:77], v0 offset:1024
	ds_read_b128 v[78:81], v0 offset:2048
	ds_read_b128 v[82:85], v0 offset:3072
	v_add_u32_e32 v0, s64, v232
	ds_read_b128 v[86:89], v0
	ds_read_b128 v[90:93], v0 offset:1024
	ds_read_b128 v[94:97], v0 offset:2048
	ds_read_b128 v[98:101], v0 offset:3072
	v_lshl_add_u64 v[194:195], s[36:37], 0, v[190:191]
	s_add_i32 m0, s50, 0xc000
	ds_read_b128 v[166:169], v236
	ds_read_b128 v[170:173], v236 offset:1024
	ds_read_b128 v[174:177], v236 offset:2048
	ds_read_b128 v[178:181], v236 offset:3072
	ds_read_b128 v[200:203], v236 offset:4096
	ds_read_b128 v[204:207], v236 offset:5120
	ds_read_b128 v[208:211], v236 offset:6144
	ds_read_b128 v[212:215], v236 offset:7168
	global_load_lds_dwordx4 v[194:195], off
	v_lshl_add_u64 v[194:195], s[36:37], 0, v[188:189]
	s_add_i32 m0, s50, 0xe000
	s_nop 0
	global_load_lds_dwordx4 v[194:195], off
	s_waitcnt vmcnt(8)
	s_waitcnt lgkmcnt(0)
	s_barrier
	s_setprio 1
	s_waitcnt lgkmcnt(0)
	v_mfma_f32_16x16x32_bf16 v[154:157], v[70:73], v[166:169], v[154:157]
	v_mfma_f32_16x16x32_bf16 v[58:61], v[78:81], v[166:169], v[58:61]
	v_mfma_f32_16x16x32_bf16 v[142:145], v[70:73], v[174:177], v[142:145]
	v_mfma_f32_16x16x32_bf16 v[138:141], v[78:81], v[174:177], v[138:141]
	v_mfma_f32_16x16x32_bf16 v[150:153], v[70:73], v[200:203], v[150:153]
	v_mfma_f32_16x16x32_bf16 v[22:25], v[78:81], v[200:203], v[22:25]
	v_mfma_f32_16x16x32_bf16 v[162:165], v[70:73], v[208:211], v[162:165]
	v_mfma_f32_16x16x32_bf16 v[34:37], v[78:81], v[208:211], v[34:37]
	v_mfma_f32_16x16x32_bf16 v[154:157], v[74:77], v[170:173], v[154:157]
	v_mfma_f32_16x16x32_bf16 v[58:61], v[82:85], v[170:173], v[58:61]
	v_mfma_f32_16x16x32_bf16 v[142:145], v[74:77], v[178:181], v[142:145]
	v_mfma_f32_16x16x32_bf16 v[138:141], v[82:85], v[178:181], v[138:141]
	v_mfma_f32_16x16x32_bf16 v[150:153], v[74:77], v[204:207], v[150:153]
	v_mfma_f32_16x16x32_bf16 v[22:25], v[82:85], v[204:207], v[22:25]
	v_mfma_f32_16x16x32_bf16 v[162:165], v[74:77], v[212:215], v[162:165]
	v_mfma_f32_16x16x32_bf16 v[34:37], v[82:85], v[212:215], v[34:37]
	s_setprio 0
	s_setprio 1
	v_mfma_f32_16x16x32_bf16 v[66:69], v[86:89], v[166:169], v[66:69]
	v_mfma_f32_16x16x32_bf16 v[54:57], v[94:97], v[166:169], v[54:57]
	v_mfma_f32_16x16x32_bf16 v[134:137], v[86:89], v[174:177], v[134:137]
	v_mfma_f32_16x16x32_bf16 v[62:65], v[94:97], v[174:177], v[62:65]
	v_mfma_f32_16x16x32_bf16 v[146:149], v[86:89], v[200:203], v[146:149]
	v_mfma_f32_16x16x32_bf16 v[18:21], v[94:97], v[200:203], v[18:21]
	v_mfma_f32_16x16x32_bf16 v[158:161], v[86:89], v[208:211], v[158:161]
	v_mfma_f32_16x16x32_bf16 v[30:33], v[94:97], v[208:211], v[30:33]
	v_mfma_f32_16x16x32_bf16 v[66:69], v[90:93], v[170:173], v[66:69]
	v_mfma_f32_16x16x32_bf16 v[54:57], v[98:101], v[170:173], v[54:57]
	v_mfma_f32_16x16x32_bf16 v[134:137], v[90:93], v[178:181], v[134:137]
	v_mfma_f32_16x16x32_bf16 v[62:65], v[98:101], v[178:181], v[62:65]
	v_mfma_f32_16x16x32_bf16 v[146:149], v[90:93], v[204:207], v[146:149]
	v_mfma_f32_16x16x32_bf16 v[18:21], v[98:101], v[204:207], v[18:21]
	v_mfma_f32_16x16x32_bf16 v[158:161], v[90:93], v[212:215], v[158:161]
	v_mfma_f32_16x16x32_bf16 v[30:33], v[98:101], v[212:215], v[30:33]
	s_setprio 0
	s_barrier
	s_add_i32 s36, s63, s49
	v_lshl_add_u64 v[194:195], s[40:41], 0, v[182:183]
	s_mov_b32 m0, s36
	ds_read_b128 v[166:169], v236 offset:16384
	ds_read_b128 v[170:173], v236 offset:17408
	ds_read_b128 v[174:177], v236 offset:18432
	ds_read_b128 v[178:181], v236 offset:19456
	ds_read_b128 v[200:203], v236 offset:20480
	ds_read_b128 v[204:207], v236 offset:21504
	ds_read_b128 v[208:211], v236 offset:22528
	ds_read_b128 v[212:215], v236 offset:23552
	s_cmp_eq_u32 s62, s98
	s_cbranch_scc1 .Lmy_u1_s2_last
	global_load_lds_dwordx4 v[194:195], off
	s_add_i32 m0, s36, 0x2000
	s_add_u32 s36, s40, 0x40000
	v_lshl_add_u64 v[196:197], s[40:41], 0, v[186:187]
	s_addc_u32 s37, s41, 0
	s_add_i32 s63, s64, s49
	global_load_lds_dwordx4 v[196:197], off
	v_lshl_add_u64 v[216:217], s[36:37], 0, v[182:183]
	s_mov_b32 m0, s63
	v_lshl_add_u64 v[242:243], s[42:43], 0, v[184:185]
	global_load_lds_dwordx4 v[216:217], off
	v_lshl_add_u64 v[216:217], s[36:37], 0, v[186:187]
	s_add_i32 m0, s63, 0x2000
	s_nop 0
	global_load_lds_dwordx4 v[216:217], off
	v_lshl_add_u64 v[216:217], s[42:43], 0, v[2:3]
	s_mov_b32 m0, s50
	s_nop 0
	global_load_lds_dwordx4 v[216:217], off
	s_mov_b32 m0, s51
	s_nop 0
	global_load_lds_dwordx4 v[242:243], off
	s_waitcnt vmcnt(8)
.Lmy_u1_s2_join:
	s_waitcnt lgkmcnt(0)
	s_barrier
	s_setprio 1
	s_waitcnt lgkmcnt(0)
	v_mfma_f32_16x16x32_bf16 v[114:117], v[70:73], v[166:169], v[114:117]
	v_mfma_f32_16x16x32_bf16 v[38:41], v[78:81], v[166:169], v[38:41]
	v_mfma_f32_16x16x32_bf16 v[110:113], v[70:73], v[174:177], v[110:113]
	v_mfma_f32_16x16x32_bf16 v[106:109], v[78:81], v[174:177], v[106:109]
	v_mfma_f32_16x16x32_bf16 v[130:133], v[70:73], v[200:203], v[130:133]
	v_mfma_f32_16x16x32_bf16 v[6:9], v[78:81], v[200:203], v[6:9]
	v_mfma_f32_16x16x32_bf16 v[14:17], v[78:81], v[208:211], v[14:17]
	v_mfma_f32_16x16x32_bf16 v[114:117], v[74:77], v[170:173], v[114:117]
	v_mfma_f32_16x16x32_bf16 v[38:41], v[82:85], v[170:173], v[38:41]
	v_mfma_f32_16x16x32_bf16 v[110:113], v[74:77], v[178:181], v[110:113]
	v_mfma_f32_16x16x32_bf16 v[106:109], v[82:85], v[178:181], v[106:109]
	v_mfma_f32_16x16x32_bf16 v[130:133], v[74:77], v[204:207], v[130:133]
	v_mfma_f32_16x16x32_bf16 v[6:9], v[82:85], v[204:207], v[6:9]
	v_mfma_f32_16x16x32_bf16 v[70:73], v[70:73], v[208:211], v[122:125]
	v_mfma_f32_16x16x32_bf16 v[14:17], v[82:85], v[212:215], v[14:17]
	v_mfma_f32_16x16x32_bf16 v[70:73], v[74:77], v[212:215], v[70:73]
	s_setprio 0
	s_setprio 1
	v_mfma_f32_16x16x32_bf16 v[46:49], v[86:89], v[166:169], v[46:49]
	v_mfma_f32_16x16x32_bf16 v[42:45], v[94:97], v[166:169], v[42:45]
	v_mfma_f32_16x16x32_bf16 v[50:53], v[94:97], v[174:177], v[50:53]
	v_mfma_f32_16x16x32_bf16 v[10:13], v[94:97], v[200:203], v[10:13]
	v_mfma_f32_16x16x32_bf16 v[26:29], v[94:97], v[208:211], v[26:29]
	v_mfma_f32_16x16x32_bf16 v[46:49], v[90:93], v[170:173], v[46:49]
	v_mfma_f32_16x16x32_bf16 v[42:45], v[98:101], v[170:173], v[42:45]
	v_mfma_f32_16x16x32_bf16 v[74:77], v[86:89], v[174:177], v[102:105]
	v_mfma_f32_16x16x32_bf16 v[50:53], v[98:101], v[178:181], v[50:53]
	v_mfma_f32_16x16x32_bf16 v[78:81], v[86:89], v[200:203], v[126:129]
	v_mfma_f32_16x16x32_bf16 v[10:13], v[98:101], v[204:207], v[10:13]
	v_mfma_f32_16x16x32_bf16 v[82:85], v[86:89], v[208:211], v[118:121]
	v_mfma_f32_16x16x32_bf16 v[26:29], v[98:101], v[212:215], v[26:29]
	v_mfma_f32_16x16x32_bf16 v[74:77], v[90:93], v[178:181], v[74:77]
	v_mfma_f32_16x16x32_bf16 v[78:81], v[90:93], v[204:207], v[78:81]
	v_mfma_f32_16x16x32_bf16 v[82:85], v[90:93], v[212:215], v[82:85]
	s_setprio 0
	s_barrier
	s_add_i32 s63, 0, 0x18000
	v_add_u32_e32 v0, s63, v232
	s_add_i32 s64, 0, 0x1c000
	ds_read_b128 v[86:89], v0
	ds_read_b128 v[90:93], v0 offset:1024
	ds_read_b128 v[94:97], v0 offset:2048
	ds_read_b128 v[98:101], v0 offset:3072
	v_add_u32_e32 v0, s64, v232
	ds_read_b128 v[118:121], v0
	ds_read_b128 v[166:169], v0 offset:1024
	ds_read_b128 v[170:173], v0 offset:2048
	ds_read_b128 v[174:177], v0 offset:3072
	s_add_u32 s36, s42, 0x40000
	s_addc_u32 s37, s43, 0
	s_mov_b32 m0, s52
	v_lshl_add_u64 v[238:239], s[36:37], 0, v[2:3]
	ds_read_b128 v[102:105], v236 offset:32768
	ds_read_b128 v[122:125], v236 offset:33792
	ds_read_b128 v[126:129], v236 offset:34816
	ds_read_b128 v[178:181], v236 offset:35840
	ds_read_b128 v[200:203], v236 offset:36864
	ds_read_b128 v[204:207], v236 offset:37888
	ds_read_b128 v[208:211], v236 offset:38912
	ds_read_b128 v[212:215], v236 offset:39936
	s_cmp_eq_u32 s62, 12
	s_cbranch_scc1 .Lmy_u1_s3_last
	global_load_lds_dwordx4 v[238:239], off
	v_lshl_add_u64 v[238:239], s[36:37], 0, v[184:185]
	s_mov_b32 m0, s53
	s_nop 0
	global_load_lds_dwordx4 v[238:239], off
	s_waitcnt vmcnt(8)
.Lmy_u1_s3_join:
	s_waitcnt lgkmcnt(0)
	s_barrier
	s_setprio 1
	s_waitcnt lgkmcnt(0)
	v_mfma_f32_16x16x32_bf16 v[154:157], v[86:89], v[102:105], v[154:157]
	v_mfma_f32_16x16x32_bf16 v[58:61], v[94:97], v[102:105], v[58:61]
	v_mfma_f32_16x16x32_bf16 v[142:145], v[86:89], v[126:129], v[142:145]
	v_mfma_f32_16x16x32_bf16 v[138:141], v[94:97], v[126:129], v[138:141]
	v_mfma_f32_16x16x32_bf16 v[150:153], v[86:89], v[200:203], v[150:153]
	v_mfma_f32_16x16x32_bf16 v[22:25], v[94:97], v[200:203], v[22:25]
	v_mfma_f32_16x16x32_bf16 v[162:165], v[86:89], v[208:211], v[162:165]
	v_mfma_f32_16x16x32_bf16 v[34:37], v[94:97], v[208:211], v[34:37]
	v_mfma_f32_16x16x32_bf16 v[154:157], v[90:93], v[122:125], v[154:157]
	v_mfma_f32_16x16x32_bf16 v[58:61], v[98:101], v[122:125], v[58:61]
	v_mfma_f32_16x16x32_bf16 v[142:145], v[90:93], v[178:181], v[142:145]
	v_mfma_f32_16x16x32_bf16 v[138:141], v[98:101], v[178:181], v[138:141]
	v_mfma_f32_16x16x32_bf16 v[150:153], v[90:93], v[204:207], v[150:153]
	v_mfma_f32_16x16x32_bf16 v[22:25], v[98:101], v[204:207], v[22:25]
	v_mfma_f32_16x16x32_bf16 v[162:165], v[90:93], v[212:215], v[162:165]
	v_mfma_f32_16x16x32_bf16 v[34:37], v[98:101], v[212:215], v[34:37]
	s_setprio 0
	s_setprio 1
	v_mfma_f32_16x16x32_bf16 v[66:69], v[118:121], v[102:105], v[66:69]
	v_mfma_f32_16x16x32_bf16 v[54:57], v[170:173], v[102:105], v[54:57]
	v_mfma_f32_16x16x32_bf16 v[102:105], v[118:121], v[126:129], v[134:137]
	v_mfma_f32_16x16x32_bf16 v[134:137], v[166:169], v[178:181], v[102:105]
	v_mfma_f32_16x16x32_bf16 v[102:105], v[118:121], v[200:203], v[146:149]
	v_mfma_f32_16x16x32_bf16 v[62:65], v[170:173], v[126:129], v[62:65]
	v_mfma_f32_16x16x32_bf16 v[146:149], v[166:169], v[204:207], v[102:105]
	v_mfma_f32_16x16x32_bf16 v[18:21], v[170:173], v[200:203], v[18:21]
	v_mfma_f32_16x16x32_bf16 v[102:105], v[118:121], v[208:211], v[158:161]
	v_mfma_f32_16x16x32_bf16 v[30:33], v[170:173], v[208:211], v[30:33]
	v_mfma_f32_16x16x32_bf16 v[66:69], v[166:169], v[122:125], v[66:69]
	v_mfma_f32_16x16x32_bf16 v[54:57], v[174:177], v[122:125], v[54:57]
	v_mfma_f32_16x16x32_bf16 v[62:65], v[174:177], v[178:181], v[62:65]
	v_mfma_f32_16x16x32_bf16 v[18:21], v[174:177], v[204:207], v[18:21]
	v_mfma_f32_16x16x32_bf16 v[158:161], v[166:169], v[212:215], v[102:105]
	v_mfma_f32_16x16x32_bf16 v[30:33], v[174:177], v[212:215], v[30:33]
	s_setprio 0
	s_barrier
	s_add_i32 s36, s63, s49
	v_lshl_add_u64 v[122:123], v[194:195], 0, s[96:97]
	s_mov_b32 m0, s36
	ds_read_b128 v[102:105], v236 offset:49152
	ds_read_b128 v[126:129], v236 offset:50176
	ds_read_b128 v[178:181], v236 offset:51200
	ds_read_b128 v[200:203], v236 offset:52224
	ds_read_b128 v[204:207], v236 offset:53248
	ds_read_b128 v[208:211], v236 offset:54272
	ds_read_b128 v[212:215], v236 offset:55296
	ds_read_b128 v[238:241], v236 offset:56320
	s_cmp_eq_u32 s62, 12
	s_cbranch_scc1 .Lmy_u1_s4_last
	global_load_lds_dwordx4 v[122:123], off
	s_add_i32 m0, s36, 0x2000
	s_add_u32 s36, s40, 0x40080
	v_lshl_add_u64 v[122:123], v[196:197], 0, s[96:97]
	s_addc_u32 s37, s41, 0
	s_add_i32 s40, s64, s49
	global_load_lds_dwordx4 v[122:123], off
	v_lshl_add_u64 v[122:123], s[36:37], 0, v[182:183]
	s_mov_b32 m0, s40
	s_nop 0
	global_load_lds_dwordx4 v[122:123], off
	v_lshl_add_u64 v[122:123], s[36:37], 0, v[186:187]
	s_add_i32 m0, s40, 0x2000
	s_nop 0
	global_load_lds_dwordx4 v[122:123], off
	v_lshl_add_u64 v[122:123], v[216:217], 0, s[96:97]
	s_mov_b32 m0, s55
	s_nop 0
	global_load_lds_dwordx4 v[122:123], off
	v_lshl_add_u64 v[122:123], v[242:243], 0, s[96:97]
	s_mov_b32 m0, s56
	s_nop 0
	global_load_lds_dwordx4 v[122:123], off
	s_waitcnt vmcnt(8)
.Lmy_u1_s4_join:
	s_waitcnt lgkmcnt(0)
	s_barrier
	s_setprio 1
	s_waitcnt lgkmcnt(0)
	v_mfma_f32_16x16x32_bf16 v[114:117], v[86:89], v[102:105], v[114:117]
	v_mfma_f32_16x16x32_bf16 v[38:41], v[94:97], v[102:105], v[38:41]
	v_mfma_f32_16x16x32_bf16 v[110:113], v[86:89], v[178:181], v[110:113]
	v_mfma_f32_16x16x32_bf16 v[106:109], v[94:97], v[178:181], v[106:109]
	v_mfma_f32_16x16x32_bf16 v[122:125], v[86:89], v[204:207], v[130:133]
	v_mfma_f32_16x16x32_bf16 v[6:9], v[94:97], v[204:207], v[6:9]
	v_mfma_f32_16x16x32_bf16 v[70:73], v[86:89], v[212:215], v[70:73]
	v_mfma_f32_16x16x32_bf16 v[14:17], v[94:97], v[212:215], v[14:17]
	v_mfma_f32_16x16x32_bf16 v[114:117], v[90:93], v[126:129], v[114:117]
	v_mfma_f32_16x16x32_bf16 v[38:41], v[98:101], v[126:129], v[38:41]
	v_mfma_f32_16x16x32_bf16 v[110:113], v[90:93], v[200:203], v[110:113]
	v_mfma_f32_16x16x32_bf16 v[106:109], v[98:101], v[200:203], v[106:109]
	v_mfma_f32_16x16x32_bf16 v[130:133], v[90:93], v[208:211], v[122:125]
	v_mfma_f32_16x16x32_bf16 v[6:9], v[98:101], v[208:211], v[6:9]
	v_mfma_f32_16x16x32_bf16 v[122:125], v[90:93], v[238:241], v[70:73]
	v_mfma_f32_16x16x32_bf16 v[14:17], v[98:101], v[238:241], v[14:17]
	s_setprio 0
	s_setprio 1
	v_mfma_f32_16x16x32_bf16 v[70:73], v[118:121], v[178:181], v[74:77]
	v_mfma_f32_16x16x32_bf16 v[46:49], v[118:121], v[102:105], v[46:49]
	v_mfma_f32_16x16x32_bf16 v[42:45], v[170:173], v[102:105], v[42:45]
	v_mfma_f32_16x16x32_bf16 v[102:105], v[166:169], v[200:203], v[70:73]
	v_mfma_f32_16x16x32_bf16 v[70:73], v[118:121], v[204:207], v[78:81]
	v_mfma_f32_16x16x32_bf16 v[46:49], v[166:169], v[126:129], v[46:49]
	v_mfma_f32_16x16x32_bf16 v[42:45], v[174:177], v[126:129], v[42:45]
	v_mfma_f32_16x16x32_bf16 v[50:53], v[170:173], v[178:181], v[50:53]
	v_mfma_f32_16x16x32_bf16 v[126:129], v[166:169], v[208:211], v[70:73]
	v_mfma_f32_16x16x32_bf16 v[10:13], v[170:173], v[204:207], v[10:13]
	v_mfma_f32_16x16x32_bf16 v[70:73], v[118:121], v[212:215], v[82:85]
	v_mfma_f32_16x16x32_bf16 v[26:29], v[170:173], v[212:215], v[26:29]
	v_mfma_f32_16x16x32_bf16 v[50:53], v[174:177], v[200:203], v[50:53]
	v_mfma_f32_16x16x32_bf16 v[10:13], v[174:177], v[208:211], v[10:13]
	v_mfma_f32_16x16x32_bf16 v[118:121], v[166:169], v[238:241], v[70:73]
	v_mfma_f32_16x16x32_bf16 v[26:29], v[174:177], v[238:241], v[26:29]
	s_setprio 0
	s_barrier
	s_add_i32 s62, s62, 2
	s_add_u32 s60, s60, 0x100
	s_addc_u32 s61, s61, 0
	s_cmp_gt_u32 s62, 13
	s_mov_b64 s[36:37], s[38:39]
	s_cbranch_scc0 .LBB0_213
	s_and_b64 vcc, exec, s[20:21]
	s_cbranch_vccz .LBB0_216
	s_barrier

.LBB0_240:
	s_or_b64 exec, exec, s[34:35]
	s_cmp_lg_u64 s[6:7], 0
	s_cbranch_scc0 .Lmy_u1_nodefer
	s_add_u32 s40, s26, 0x40000
	s_addc_u32 s41, s27, 0
	s_mov_b32 m0, s52
	v_lshl_add_u64 v[194:195], s[40:41], 0, v[2:3]
	global_load_lds_dwordx4 v[194:195], off
	s_mov_b32 m0, s53
	v_lshl_add_u64 v[196:197], s[40:41], 0, v[184:185]
	global_load_lds_dwordx4 v[196:197], off
	s_add_u32 s60, s28, s96
	s_addc_u32 s61, s29, s97
	s_add_i32 s63, s49, 0x18000
	s_mov_b32 m0, s63
	v_lshl_add_u64 v[194:195], s[60:61], 0, v[182:183]
	global_load_lds_dwordx4 v[194:195], off
	s_add_i32 m0, s63, 0x2000
	v_lshl_add_u64 v[196:197], s[60:61], 0, v[186:187]
	global_load_lds_dwordx4 v[196:197], off
	s_add_u32 s60, s28, 0x40080
	s_addc_u32 s61, s29, 0
	s_add_i32 s63, s49, 0x1c000
	s_mov_b32 m0, s63
	v_lshl_add_u64 v[194:195], s[60:61], 0, v[182:183]
	global_load_lds_dwordx4 v[194:195], off
	s_add_i32 m0, s63, 0x2000
	v_lshl_add_u64 v[196:197], s[60:61], 0, v[186:187]
	global_load_lds_dwordx4 v[196:197], off
	s_add_u32 s60, s26, s96
	s_addc_u32 s61, s27, s97
	s_mov_b32 m0, s55
	v_lshl_add_u64 v[194:195], s[60:61], 0, v[2:3]
	global_load_lds_dwordx4 v[194:195], off
	s_mov_b32 m0, s56
	v_lshl_add_u64 v[196:197], s[60:61], 0, v[184:185]
	global_load_lds_dwordx4 v[196:197], off
.Lmy_u1_nodefer:
	v_mov_b32_e32 v170, v1
	v_mov_b32_e32 v171, v1
	v_mov_b32_e32 v106, v1
	v_mov_b32_dpp v170, v150 row_shr:1 row_mask:0xf bank_mask:0xf
	v_mov_b32_e32 v107, v1
	v_mov_b32_dpp v171, v151 row_shr:1 row_mask:0xf bank_mask:0xf
	v_mov_b32_dpp v106, v162 row_shr:1 row_mask:0xf bank_mask:0xf
	v_mov_b32_dpp v107, v163 row_shr:1 row_mask:0xf bank_mask:0xf
	v_pk_fma_f32 v[170:171], v[74:75], v[170:171], v[78:79]
	v_mov_b32_e32 v172, v1
	v_pk_fma_f32 v[170:171], v[98:99], v[106:107], v[170:171]
	v_mov_b32_e32 v173, v1
	v_pk_fma_f32 v[174:175], v[94:95], v[166:167], v[170:171]
	v_mov_b32_e32 v178, v1
	v_mul_f32_e32 v0, v174, v174
	v_fmamk_f32 v0, v0, 0xbdd2d3e2, v220
	v_mul_f32_e32 v0, v174, v0
	v_exp_f32_e32 v0, v0
	v_mov_b32_e32 v179, v1
	v_mov_b32_e32 v108, v1
	v_mov_b32_dpp v172, v152 row_shr:1 row_mask:0xf bank_mask:0xf
	v_add_f32_e32 v0, 1.0, v0
	v_rcp_f32_e32 v0, v0
	v_mov_b32_e32 v109, v1
	v_mov_b32_dpp v173, v153 row_shr:1 row_mask:0xf bank_mask:0xf
	v_mov_b32_e32 v170, v1
	v_mul_f32_e32 v0, v174, v0
	v_mul_f32_e32 v174, v175, v175
	v_fmamk_f32 v174, v174, 0xbdd2d3e2, v220
	v_mul_f32_e32 v174, v175, v174
	v_exp_f32_e32 v174, v174
	v_mov_b32_dpp v178, v146 row_shr:1 row_mask:0xf bank_mask:0xf
	v_mov_b32_e32 v171, v1
	v_mov_b32_dpp v179, v147 row_shr:1 row_mask:0xf bank_mask:0xf
	v_add_f32_e32 v174, 1.0, v174
	v_rcp_f32_e32 v174, v174
	v_mov_b32_dpp v108, v164 row_shr:1 row_mask:0xf bank_mask:0xf
	v_mov_b32_dpp v109, v165 row_shr:1 row_mask:0xf bank_mask:0xf
	v_pk_fma_f32 v[172:173], v[76:77], v[172:173], v[80:81]
	v_mov_b32_dpp v170, v158 row_shr:1 row_mask:0xf bank_mask:0xf
	v_mov_b32_dpp v171, v159 row_shr:1 row_mask:0xf bank_mask:0xf
	v_pk_fma_f32 v[178:179], v[86:87], v[178:179], v[90:91]
	v_pk_fma_f32 v[172:173], v[100:101], v[108:109], v[172:173]
	v_pk_fma_f32 v[178:179], v[82:83], v[170:171], v[178:179]
	v_pk_fma_f32 v[176:177], v[96:97], v[168:169], v[172:173]
	v_pk_fma_f32 v[178:179], v[70:71], v[154:155], v[178:179]
	v_mul_f32_e32 v174, v175, v174
	v_mul_f32_e32 v0, v0, v178
	v_mul_f32_e32 v174, v174, v179
	v_mul_f32_e32 v175, v177, v177
	v_cvt_pk_bf16_f32 v174, v0, v174
	v_mul_f32_e32 v0, v176, v176
	v_fmamk_f32 v175, v175, 0xbdd2d3e2, v220
	v_fmamk_f32 v0, v0, 0xbdd2d3e2, v220
	v_mul_f32_e32 v175, v177, v175
	v_mul_f32_e32 v0, v176, v0
	v_exp_f32_e32 v175, v175
	v_exp_f32_e32 v0, v0
	v_mov_b32_e32 v180, v1
	v_mov_b32_e32 v181, v1
	v_add_f32_e32 v175, 1.0, v175
	v_add_f32_e32 v0, 1.0, v0
	v_rcp_f32_e32 v175, v175
	v_mov_b32_e32 v172, v1
	v_mov_b32_dpp v180, v148 row_shr:1 row_mask:0xf bank_mask:0xf
	v_mov_b32_e32 v173, v1
	v_mov_b32_dpp v181, v149 row_shr:1 row_mask:0xf bank_mask:0xf
	v_rcp_f32_e32 v0, v0
	v_mov_b32_dpp v172, v160 row_shr:1 row_mask:0xf bank_mask:0xf
	v_mov_b32_dpp v173, v161 row_shr:1 row_mask:0xf bank_mask:0xf
	v_pk_fma_f32 v[180:181], v[88:89], v[180:181], v[92:93]
	v_mul_f32_e32 v175, v177, v175
	v_pk_fma_f32 v[180:181], v[84:85], v[172:173], v[180:181]
	v_mul_f32_e32 v0, v176, v0
	v_pk_fma_f32 v[180:181], v[72:73], v[156:157], v[180:181]
	s_nop 0
	v_mul_f32_e32 v175, v175, v181
	v_mul_f32_e32 v0, v0, v180
	v_cvt_pk_bf16_f32 v175, v0, v175
	s_and_saveexec_b64 s[30:31], s[4:5]
	s_cbranch_execz .LBB0_242
	s_movk_i32 s23, 0xc00
	v_mul_lo_u32 v0, v237, s23
	v_add_lshl_u32 v0, v0, v192, 1
	v_lshl_add_u64 v[176:177], s[8:9], 0, v[0:1]
	global_store_dwordx2 v[176:177], v[174:175], off

	.amdhsa_kernel _Z10fwd_kernel5KArgs
		.amdhsa_group_segment_fixed_size 0
		.amdhsa_private_segment_fixed_size 0
		.amdhsa_kernarg_size 560
		.amdhsa_user_sgpr_count 2
		.amdhsa_user_sgpr_dispatch_ptr 0
		.amdhsa_user_sgpr_queue_ptr 0
		.amdhsa_user_sgpr_kernarg_segment_ptr 1
		.amdhsa_user_sgpr_dispatch_id 0
		.amdhsa_user_sgpr_kernarg_preload_length 0
		.amdhsa_user_sgpr_kernarg_preload_offset 0
		.amdhsa_user_sgpr_private_segment_size 0
		.amdhsa_uses_dynamic_stack 0
		.amdhsa_enable_private_segment 0
		.amdhsa_system_sgpr_workgroup_id_x 1
		.amdhsa_system_sgpr_workgroup_id_y 0
		.amdhsa_system_sgpr_workgroup_id_z 0
		.amdhsa_system_sgpr_workgroup_info 0
		.amdhsa_system_vgpr_workitem_id 2
		.amdhsa_next_free_vgpr 256
		.amdhsa_next_free_sgpr 102
		.amdhsa_accum_offset 256
		.amdhsa_reserve_vcc 1
		.amdhsa_float_round_mode_32 0
		.amdhsa_float_round_mode_16_64 0
		.amdhsa_float_denorm_mode_32 3
		.amdhsa_float_denorm_mode_16_64 3
		.amdhsa_dx10_clamp 1
		.amdhsa_ieee_mode 1
		.amdhsa_fp16_overflow 0
		.amdhsa_tg_split 0
		.amdhsa_exception_fp_ieee_invalid_op 0
		.amdhsa_exception_fp_denorm_src 0
		.amdhsa_exception_fp_ieee_div_zero 0
		.amdhsa_exception_fp_ieee_overflow 0
		.amdhsa_exception_fp_ieee_underflow 0
		.amdhsa_exception_fp_ieee_inexact 0
		.amdhsa_exception_int_div_zero 0
	.end_amdhsa_kernel

amdhsa.kernels:
  - .agpr_count:     0
    .args:
      - .offset:         0
        .size:           304
        .value_kind:     by_value
      - .offset:         304
        .size:           4
        .value_kind:     hidden_block_count_x
      - .offset:         308
        .size:           4
        .value_kind:     hidden_block_count_y
      - .offset:         312
        .size:           4
        .value_kind:     hidden_block_count_z
      - .offset:         316
        .size:           2
        .value_kind:     hidden_group_size_x
      - .offset:         318
        .size:           2
        .value_kind:     hidden_group_size_y
      - .offset:         320
        .size:           2
        .value_kind:     hidden_group_size_z
      - .offset:         322
        .size:           2
        .value_kind:     hidden_remainder_x
      - .offset:         324
        .size:           2
        .value_kind:     hidden_remainder_y
      - .offset:         326
        .size:           2
        .value_kind:     hidden_remainder_z
      - .offset:         344
        .size:           8
        .value_kind:     hidden_global_offset_x
      - .offset:         352
        .size:           8
        .value_kind:     hidden_global_offset_y
      - .offset:         360
        .size:           8
        .value_kind:     hidden_global_offset_z
      - .offset:         368
        .size:           2
        .value_kind:     hidden_grid_dims
      - .offset:         392
        .size:           8
        .value_kind:     hidden_multigrid_sync_arg
      - .offset:         424
        .size:           4
        .value_kind:     hidden_dynamic_lds_size
    .group_segment_fixed_size: 0
    .kernarg_segment_align: 8
    .kernarg_segment_size: 560
    .language:       OpenCL C
    .language_version:
      - 2
      - 0
    .max_flat_workgroup_size: 512
    .name:           _Z10fwd_kernel5KArgs
    .private_segment_fixed_size: 0
    .sgpr_count:     108
    .sgpr_spill_count: 93
    .symbol:         _Z10fwd_kernel5KArgs.kd
    .uniform_work_group_size: 1
    .uses_dynamic_stack: false
    .vgpr_count:     256
    .vgpr_spill_count: 0
    .wavefront_size: 64
